# P0: half of the workgroups (bit 3 of the block id) convert their weight tiles before their x rows
# baseline (speedup 1.0000x reference)
; #define LAS __attribute__((address_space(3)))
; __device__ __forceinline__ unsigned xb_add(unsigned* p, unsigned v) { return __hip_atomic_fetch_add(p, v, __ATOMIC_RELAXED, __HIP_MEMORY_SCOPE_AGENT); }
; __device__ __forceinline__ unsigned xb_xcc_id() { return (unsigned)__builtin_amdgcn_s_getreg((3 << 11) | 20) & 0xFu; }
; __device__ __forceinline__ XcdBarrier xcd_barrier_post(unsigned* bar, volatile LAS unsigned* st) {
;     XcdBarrier b; b.bar = bar; b.x = xb_xcc_id(); b.st = st;
;     if (threadIdx.x == 0) (void)xb_add(&bar[XB_XCNT(b.x)], 1u);
;     return b;
; __global__ void __launch_bounds__(512, 2) mega_fwd(Params p) {
;     ...
;     const int lo = p.ph_lo, hi = p.ph_hi;
;     ...
;     unsigned char* ws = p.ws;
;     volatile LAS unsigned* stw = (volatile LAS unsigned*)(lds + LDS_STAGE);
;     if (threadIdx.x < 4) stw[threadIdx.x] = 0u;
;     __syncthreads();
;     XcdBarrier bar; bar.bar = (unsigned*)(ws + OFF_BAR); bar.x = 0; bar.st = stw;
;     if (hi - lo > 1) bar = xcd_barrier_post((unsigned*)(ws + OFF_BAR), stw);
.Lmy_prio_done:
	s_mov_b32 s101, 0
	s_load_dwordx4 s[28:31], s[0:1], 0xa0
	s_load_dwordx2 s[34:35], s[0:1], 0xb0
	v_cmp_gt_u32_e32 vcc, 4, v0
	s_and_saveexec_b64 s[4:5], vcc
	v_lshl_add_u32 v1, v0, 2, 0
	v_add_u32_e32 v1, 0x20000, v1
	v_mov_b32_e32 v2, 0
	ds_write_b32 v1, v2
	s_or_b64 exec, exec, s[4:5]
	s_load_dwordx16 s[12:27], s[0:1], 0x0
	s_waitcnt lgkmcnt(0)
	s_add_u32 s60, s30, 0xb4b8000
	s_addc_u32 s61, s31, 0
	s_sub_i32 s3, s35, s34
	s_cmp_lt_i32 s3, 2
	s_mov_b32 s33, 0
	s_barrier
	s_cbranch_scc1 .LBB0_7
	s_getreg_b32 s3, hwreg(HW_REG_XCC_ID, 0, 4)
	s_and_b32 s33, s3, 15
	v_cmp_eq_u32_e32 vcc, 0, v0
	s_and_saveexec_b64 s[4:5], vcc
	s_cbranch_execz .LBB0_6
	s_mov_b64 s[6:7], exec
	v_mbcnt_lo_u32_b32 v1, s6, 0
	v_mbcnt_hi_u32_b32 v1, s7, v1
	v_cmp_eq_u32_e32 vcc, 0, v1
	s_and_b64 s[8:9], exec, vcc
	s_mov_b64 exec, s[8:9]
	s_cbranch_execz .LBB0_6
	s_lshl_b32 s3, s33, 8
	s_bcnt1_i32_b64 s6, s[6:7]
	v_mov_b32_e32 v1, s3
	v_mov_b32_e32 v2, s6
	global_atomic_add v1, v2, s[60:61] offset:1024

; __device__ __forceinline__ f32x4 ldnt(const f32x4* p) { return __builtin_nontemporal_load(p); }
; __device__ __forceinline__ u32x4 ldnt(const u32x4* p) { return __builtin_nontemporal_load(p); }
; __device__ __forceinline__ void prep_phase(const Params& p, LAS unsigned char* lds) {
;     const int tid = threadIdx.x, lane = tid & 63, wid = tid >> 6;
;     {
;         const int gw = blockIdx.x * 8 + wid, nw = gridDim.x * 8;
;         f32x4 xv[4];
;         if (gw < MTOT) { const float* xs = gw < MP ? p.in[0] + (size_t)gw * 1024 : p.in[1] + (size_t)(gw - MP) * 1024;
; #pragma unroll
;             for (int i = 0; i < 4; ++i) xv[i] = ldnt((const f32x4*)(xs + i * 256 + lane * 4)); }
;         for (int row = gw; row < MTOT; row += nw) {
;             f32x4 cv[4];
; #pragma unroll
;             for (int i = 0; i < 4; ++i) cv[i] = xv[i];
;             const int nr = row + nw;
;             if (nr < MTOT) { const float* xs = nr < MP ? p.in[0] + (size_t)nr * 1024 : p.in[1] + (size_t)(nr - MP) * 1024;
; #pragma unroll
;                 for (int i = 0; i < 4; ++i) xv[i] = ldnt((const f32x4*)(xs + i * 256 + lane * 4)); }
.LBB0_7:
	s_cmp_lt_i32 s34, 1
	s_cselect_b64 s[4:5], -1, 0
	s_cmp_gt_i32 s35, 0
	s_cselect_b64 s[6:7], -1, 0
	s_and_b64 s[10:11], s[4:5], s[6:7]
	s_andn2_b64 vcc, exec, s[10:11]
	s_cbranch_vccnz .LBB0_90
	s_load_dword s3, s[0:1], 0xb8
	s_waitcnt lgkmcnt(0)
	s_cmp_lg_u32 s3, 0x100
	s_cbranch_scc1 .Lmy_p0x
	s_bitcmp1_b32 s2, 3
	s_cbranch_scc0 .Lmy_p0x
	s_mov_b32 s101, 1
	s_branch .Lmy_p0tiles
.Lmy_p0x:
	v_lshrrev_b32_e32 v1, 6, v0
	v_lshl_or_b32 v34, s2, 3, v1
	s_movk_i32 s52, 0x4080
	v_cmp_gt_i32_e32 vcc, s52, v34
	s_and_saveexec_b64 s[62:63], vcc
	s_cbranch_execz .LBB0_15
	s_movk_i32 s53, 0x4000
	v_add_u32_e32 v2, 0xffffc000, v34
	v_ashrrev_i32_e32 v35, 31, v34
	v_cmp_gt_i32_e32 vcc, s53, v34
	v_mov_b32_e32 v4, s15
	v_mov_b32_e32 v5, s13
	v_cndmask_b32_e32 v3, 0, v35, vcc
	v_cndmask_b32_e32 v2, v2, v34, vcc
	v_cndmask_b32_e32 v5, v4, v5, vcc
	v_mov_b32_e32 v4, s14
	v_mov_b32_e32 v6, s12
	v_and_b32_e32 v1, 63, v0
	v_mov_b32_e32 v37, 0
	v_cndmask_b32_e32 v4, v4, v6, vcc
	v_lshlrev_b64 v[2:3], 12, v[2:3]
	v_lshl_add_u64 v[2:3], v[4:5], 0, v[2:3]
	v_lshlrev_b32_e32 v4, 4, v1
	v_mov_b32_e32 v5, v37
	v_lshl_add_u64 v[2:3], v[2:3], 0, v[4:5]
	global_load_dwordx4 v[14:17], v[2:3], off nt
	global_load_dwordx4 v[6:9], v[2:3], off offset:1024 nt
	global_load_dwordx4 v[10:13], v[2:3], off offset:2048 nt
	s_nop 0
	global_load_dwordx4 v[2:5], v[2:3], off offset:3072 nt
	s_waitcnt lgkmcnt(0)
	s_lshl_b32 s64, s3, 3
	v_lshlrev_b32_e32 v36, 2, v1
	v_lshlrev_b64 v[18:19], 6, v[34:35]
	v_lshlrev_b64 v[40:41], 11, v[34:35]
	v_cmp_gt_u32_e32 vcc, 16, v1
	v_cmp_eq_u32_e64 s[4:5], 0, v1
	v_lshl_add_u64 v[18:19], v[18:19], 0, v[36:37]
	s_mov_b64 s[6:7], 0xaea0000
	s_ashr_i32 s65, s64, 31
	v_lshl_or_b32 v40, v1, 3, v40
	v_mbcnt_lo_u32_b32 v1, -1, 0
	v_lshl_add_u64 v[38:39], v[18:19], 0, s[6:7]
	s_lshl_b64 s[66:67], s[64:65], 6
	s_lshl_b64 s[68:69], s[64:65], 11
	s_mov_b64 s[70:71], 0
	s_movk_i32 s54, 0x407f
	v_lshlrev_b32_e32 v36, 2, v36
	s_mov_b32 s55, 0x2d60000
	v_mbcnt_hi_u32_b32 v1, -1, v1
	s_branch .LBB0_11

; #define LAS __attribute__((address_space(3)))
; __device__ __forceinline__ f32x4 ldnt(const f32x4* p) { return __builtin_nontemporal_load(p); }
; __device__ __forceinline__ u32x4 ldnt(const u32x4* p) { return __builtin_nontemporal_load(p); }
; __device__ __forceinline__ void prep_tiles(const Params& p, LAS unsigned char* lds, int t_first, int t_end, int stride) {
;     const int tid = threadIdx.x;
;     LAS float* tl = (LAS float*)lds;
;     f32x4 pf[8];
;     if (t_first < t_end) { const float* src; bf16_t* dst; const float* gain; int K, N, k0, n0, drow0; WJOB_DECODE(t_first, src, dst, gain, K, N, k0, n0, drow0);
;         (void)dst; (void)gain; (void)K; (void)drow0;
; #pragma unroll
;         for (int i = 0; i < 8; ++i) { const int e = tid + 512 * i; pf[i] = ldnt((const f32x4*)(src + (size_t)(k0 + (e >> 5)) * N + n0 + (e & 31) * 4)); } }
.LBB0_15:
	s_or_b64 exec, exec, s[62:63]
	s_cmp_eq_u32 s101, 2
	s_cbranch_scc1 .LBB0_90
.Lmy_p0tiles:
	s_cmpk_lt_i32 s2, 0x2d4
	s_cselect_b64 s[4:5], -1, 0
	s_cmpk_gt_i32 s2, 0x2d3
	s_cbranch_scc1 .LBB0_39
	s_cmpk_lt_i32 s2, 0x80
	s_cbranch_scc1 .LBB0_22
	s_cmpk_gt_u32 s2, 0xbf
	s_cbranch_scc0 .LBB0_23
	s_cmpk_gt_u32 s2, 0x16f
	s_cbranch_scc0 .LBB0_24
	s_cmpk_gt_u32 s2, 0x21f
	s_cbranch_scc0 .LBB0_25
	s_cmpk_gt_u32 s2, 0x2cf
	s_cbranch_scc0 .LBB0_26
	s_load_dwordx16 s[36:51], s[0:1], 0x40
	s_add_i32 s6, s2, 0xfffffd30
	s_mov_b32 s7, 0
	s_lshl_b64 s[6:7], s[6:7], 16
	s_mov_b64 s[8:9], 0
	s_waitcnt lgkmcnt(0)
	s_add_u32 s6, s36, s6
	s_addc_u32 s7, s37, s7
	s_branch .LBB0_27

; __device__ __forceinline__ void prep_phase(const Params& p, LAS unsigned char* lds) {
;     ...
;     }
;     prep_tiles(p, lds, blockIdx.x, NT_L0, gridDim.x);
; }
.LBB0_90:
	s_cmp_eq_u32 s101, 1
	s_cbranch_scc0 .Lmy_p0done
	s_mov_b32 s101, 2
	s_load_dwordx4 s[12:15], s[0:1], 0x0
	s_waitcnt lgkmcnt(0)
	s_branch .Lmy_p0x
